# hoist rmsnorm gamma loads; prefetch S5 input fragments; batch S5 skip-term loads; attention LDS swizzle
# speedup vs baseline: 1.0069x; 1.0058x over previous
; __device__ __forceinline__ int fresh_tid() { int t = threadIdx.x; asm volatile("" : "+v"(t)); return t; }
; __device__ __forceinline__ void phase_norm(const float* x, const float* g, bf16_t* h) {
;     const int tid = fresh_tid(), wave = tid >> 6, lane = tid & 63;
;     for (int row = blockIdx.x * 8 + wave; row < SEQ; row += gridDim.x * 8) {
;         const f32x4* xr = (const f32x4*)(x + (size_t)row * DM) + lane;
;         f32x4 v[8]; float ss = 0.f;
; #pragma unroll
;         for (int j = 0; j < 8; ++j) { v[j] = xr[64 * j]; ss += v[j][0] * v[j][0] + v[j][1] * v[j][1] + v[j][2] * v[j][2] + v[j][3] * v[j][3]; }
;         const float rstd = rsqrtf(wave_sum(ss) * (1.f / DM) + EPS);
;         u32x2* o = (u32x2*)(h + (size_t)row * DM) + lane;
; #pragma unroll
;         for (int j = 0; j < 8; ++j) { const f32x4 gg = *((const f32x4*)g + lane + 64 * j);
.LBB0_351:
	s_mov_b32 s6, s0
	v_writelane_b32 v255, s6, 46
	s_cmp_eq_u32 s0, 0
	s_cselect_b64 s[0:1], -1, 0
	v_writelane_b32 v255, s7, 47
	v_writelane_b32 v255, s0, 48
	s_mov_b64 s[6:7], s[94:95]
	v_mov_b32_e32 v0, v250
	v_writelane_b32 v255, s1, 49
	v_readlane_b32 s0, v253, 2
	v_ashrrev_i32_e32 v2, 6, v0
	v_readlane_b32 s1, v253, 3
	v_add_u32_e32 v6, s0, v2
	s_movk_i32 s0, 0x2000
	v_cmp_gt_i32_e32 vcc, s0, v6
	s_and_saveexec_b64 s[0:1], vcc
	s_cbranch_execz .LBB0_354
	v_cmp_lt_i32_e32 vcc, v245, v187
	v_readlane_b32 s20, v255, 48
	v_readlane_b32 s21, v255, 49
	v_cndmask_b32_e32 v3, v185, v245, vcc
	v_cmp_lt_i32_e32 vcc, v204, v187
	v_lshlrev_b32_e32 v22, 2, v3
	s_and_b64 s[20:21], s[20:21], exec
	v_cndmask_b32_e32 v3, v185, v204, vcc
	v_cmp_lt_i32_e32 vcc, v181, v187
	v_lshlrev_b32_e32 v23, 2, v3
	s_cselect_b32 s20, 0, 0xe8
	v_cndmask_b32_e32 v3, v185, v181, vcc
	v_cmp_lt_i32_e32 vcc, v252, v187
	v_lshlrev_b32_e32 v24, 2, v3
	s_add_u32 s20, s6, s20
	v_cndmask_b32_e32 v3, v185, v252, vcc
	v_lshlrev_b32_e32 v25, 2, v3
	v_xor_b32_e32 v3, 16, v185
	s_addc_u32 s21, s7, 0
	v_cmp_lt_i32_e32 vcc, v3, v187
	s_load_dwordx2 s[24:25], s[6:7], 0x10
	s_nop 0
	s_load_dwordx2 s[20:21], s[20:21], 0x0
	s_nop 0
	s_load_dwordx2 s[6:7], s[6:7], 0xf0
	v_cndmask_b32_e32 v3, v185, v3, vcc
	v_readlane_b32 s30, v255, 46
	v_lshlrev_b32_e32 v26, 2, v3
	v_xor_b32_e32 v3, 32, v185
	v_readlane_b32 s31, v255, 47
	s_lshl_b32 s38, s30, 11
	v_cmp_lt_i32_e32 vcc, v3, v187
	s_lshl_b64 s[30:31], s[38:39], 2
	v_and_b32_e32 v2, 63, v0
	v_cndmask_b32_e32 v3, v185, v3, vcc
	s_waitcnt lgkmcnt(0)
	s_add_u32 s24, s24, s30
	v_lshlrev_b32_e32 v0, 4, v2
	v_lshlrev_b32_e32 v27, 2, v3
	v_lshlrev_b32_e32 v2, 3, v2
	v_mov_b32_e32 v3, v1
	s_addc_u32 s25, s25, s31
	v_lshl_add_u64 v[2:3], s[6:7], 0, v[2:3]
	s_mov_b64 s[6:7], 0x15b00000
	v_lshl_add_u64 v[10:11], v[2:3], 0, s[6:7]
	v_lshl_add_u64 v[12:13], s[24:25], 0, v[0:1]
	s_mov_b64 s[6:7], 0x1400
	v_lshl_add_u64 v[16:17], v[12:13], 0, s[6:7]
	s_mov_b64 s[6:7], 0x1800
	v_lshl_add_u64 v[18:19], v[12:13], 0, s[6:7]
	s_mov_b64 s[6:7], 0x1c00
	v_lshl_add_u64 v[8:9], s[20:21], 0, v[0:1]
	v_lshl_add_u64 v[14:15], v[12:13], 0, s[14:15]
	v_lshl_add_u64 v[20:21], v[12:13], 0, s[6:7]
	s_mov_b64 s[6:7], 0
	global_load_dwordx4 v[104:107], v[12:13], off offset:1024
	global_load_dwordx4 v[108:111], v[12:13], off offset:2048
	global_load_dwordx4 v[112:115], v[12:13], off offset:3072
	global_load_dwordx4 v[116:119], v[14:15], off
	global_load_dwordx4 v[120:123], v[16:17], off
	global_load_dwordx4 v[124:127], v[18:19], off
	global_load_dwordx4 v[128:131], v[20:21], off
; __device__ __forceinline__ unsigned cvt_pk_bf16(float lo, float hi) { unsigned r; asm volatile("s_nop 0\n\tv_cvt_pk_bf16_f32 %0, %1, %2" : "=v"(r) : "v"(lo), "v"(hi)); return r; }
; __device__ __forceinline__ void phase_norm(const float* x, const float* g, bf16_t* h) {
;     ...
;     for (int row = blockIdx.x * 8 + wave; row < SEQ; row += gridDim.x * 8) {
;         const f32x4* xr = (const f32x4*)(x + (size_t)row * DM) + lane;
;         f32x4 v[8]; float ss = 0.f;
; #pragma unroll
;         for (int j = 0; j < 8; ++j) { v[j] = xr[64 * j]; ss += v[j][0] * v[j][0] + v[j][1] * v[j][1] + v[j][2] * v[j][2] + v[j][3] * v[j][3]; }
;         const float rstd = rsqrtf(wave_sum(ss) * (1.f / DM) + EPS);
;         u32x2* o = (u32x2*)(h + (size_t)row * DM) + lane;
; #pragma unroll
;         for (int j = 0; j < 8; ++j) { const f32x4 gg = *((const f32x4*)g + lane + 64 * j);
;             u32x2 w; w.x = cvt_pk_bf16(v[j][0] * rstd * gg[0], v[j][1] * rstd * gg[1]); w.y = cvt_pk_bf16(v[j][2] * rstd * gg[2], v[j][3] * rstd * gg[3]); o[64 * j] = w; }
;     }
.LBB0_353:
	v_ashrrev_i32_e32 v7, 31, v6
	v_lshlrev_b64 v[2:3], 13, v[6:7]
	v_lshl_add_u64 v[2:3], v[8:9], 0, v[2:3]
	global_load_dwordx4 v[28:31], v[2:3], off
	global_load_dwordx4 v[32:35], v[2:3], off offset:1024
	global_load_dwordx4 v[36:39], v[2:3], off offset:2048
	global_load_dwordx4 v[40:43], v[2:3], off offset:3072
	v_add_co_u32_e32 v2, vcc, s28, v2
	s_waitcnt vmcnt(3)
	v_mul_f32_e32 v0, v29, v29
	v_addc_co_u32_e32 v3, vcc, 0, v3, vcc
	global_load_dwordx4 v[44:47], v[2:3], off
	global_load_dwordx4 v[48:51], v[2:3], off offset:1024
	global_load_dwordx4 v[52:55], v[2:3], off offset:2048
	s_nop 0
	global_load_dwordx4 v[2:5], v[2:3], off offset:3072
	s_nop 0
	global_load_dwordx4 v[56:59], v[12:13], off
	s_waitcnt vmcnt(7)
	v_mul_f32_e32 v76, v33, v33
	s_waitcnt vmcnt(6)
	v_mul_f32_e32 v77, v37, v37
	v_fmac_f32_e32 v0, v28, v28
	v_fmac_f32_e32 v76, v32, v32
	s_waitcnt vmcnt(5)
	v_mul_f32_e32 v78, v41, v41
	v_fmac_f32_e32 v77, v36, v36
	v_fmac_f32_e32 v0, v30, v30
	v_fmac_f32_e32 v76, v34, v34
	v_fmac_f32_e32 v78, v40, v40
	v_fmac_f32_e32 v77, v38, v38
	v_fmac_f32_e32 v0, v31, v31
	v_fmac_f32_e32 v76, v35, v35
	v_fmac_f32_e32 v78, v42, v42
	v_fmac_f32_e32 v77, v39, v39
	v_add_f32_e32 v0, v0, v76
	v_fmac_f32_e32 v78, v43, v43
	v_add_f32_e32 v0, v0, v77
	v_add_f32_e32 v0, v0, v78
	s_waitcnt vmcnt(4)
	v_mov_b32_e32 v62, v45
	s_waitcnt vmcnt(3)
	v_mov_b32_e32 v63, v49
	v_mov_b32_e32 v60, v44
	v_mov_b32_e32 v61, v48
	v_pk_mul_f32 v[62:63], v[62:63], v[62:63]
	v_mov_b32_e32 v64, v46
	v_mov_b32_e32 v65, v50
	s_waitcnt vmcnt(2)
	v_mov_b32_e32 v70, v53
	s_waitcnt vmcnt(1)
	v_mov_b32_e32 v71, v3
	v_pk_fma_f32 v[60:61], v[60:61], v[60:61], v[62:63]
	v_mov_b32_e32 v66, v47
	v_mov_b32_e32 v67, v51
	v_mov_b32_e32 v68, v52
	v_mov_b32_e32 v69, v2
	v_pk_mul_f32 v[70:71], v[70:71], v[70:71]
	v_pk_fma_f32 v[60:61], v[64:65], v[64:65], v[60:61]
	v_mov_b32_e32 v72, v54
	v_mov_b32_e32 v73, v4
	v_pk_fma_f32 v[62:63], v[68:69], v[68:69], v[70:71]
	v_pk_fma_f32 v[60:61], v[66:67], v[66:67], v[60:61]
	v_mov_b32_e32 v74, v55
	v_mov_b32_e32 v75, v5
	v_pk_fma_f32 v[62:63], v[72:73], v[72:73], v[62:63]
	v_add_f32_e32 v0, v0, v60
	v_pk_fma_f32 v[62:63], v[74:75], v[74:75], v[62:63]
	v_add_f32_e32 v0, v0, v61
	v_add_f32_e32 v0, v0, v62
	v_add_f32_e32 v0, v0, v63
	ds_bpermute_b32 v60, v22, v0
	s_waitcnt lgkmcnt(0)
	v_add_f32_e32 v0, v0, v60
	ds_bpermute_b32 v60, v23, v0
	s_waitcnt lgkmcnt(0)
	v_add_f32_e32 v0, v0, v60
	ds_bpermute_b32 v60, v24, v0
	s_waitcnt lgkmcnt(0)
	v_add_f32_e32 v0, v0, v60
	ds_bpermute_b32 v60, v25, v0
	s_waitcnt lgkmcnt(0)
	v_add_f32_e32 v0, v0, v60
	ds_bpermute_b32 v60, v26, v0
	s_waitcnt lgkmcnt(0)
	v_add_f32_e32 v0, v0, v60
	ds_bpermute_b32 v60, v27, v0
	s_waitcnt lgkmcnt(0)
	v_add_f32_e32 v0, v0, v60
	v_fmamk_f32 v0, v0, 0x3a000000, v242
	v_mul_f32_e32 v60, 0x4b800000, v0
	v_cmp_gt_f32_e32 vcc, s29, v0
	s_nop 1
	v_cndmask_b32_e32 v0, v0, v60, vcc
	v_rsq_f32_e32 v0, v0
	v_lshlrev_b64 v[60:61], 12, v[6:7]
	v_lshl_add_u64 v[60:61], v[10:11], 0, v[60:61]
	v_add_u32_e32 v6, s60, v6
	v_mul_f32_e32 v7, 0x45800000, v0
	v_cndmask_b32_e32 v0, v0, v7, vcc
	v_mul_f32_e32 v7, v28, v0
	v_mul_f32_e32 v28, v29, v0
	v_mul_f32_e32 v29, v30, v0
	v_mul_f32_e32 v30, v31, v0
	s_waitcnt vmcnt(0)
	v_mul_f32_e32 v28, v57, v28
	v_mul_f32_e32 v29, v58, v29
	v_mul_f32_e32 v7, v56, v7
	v_mul_f32_e32 v30, v59, v30
	s_nop 0
	v_cvt_pk_bf16_f32 v28, v7, v28
	s_nop 0
	v_cvt_pk_bf16_f32 v29, v29, v30
	global_store_dwordx2 v[60:61], v[28:29], off
	v_mul_f32_e32 v7, v32, v0
	v_mul_f32_e32 v32, v33, v0
	v_mul_f32_e32 v33, v34, v0
	v_mul_f32_e32 v34, v35, v0
	v_cmp_lt_i32_e32 vcc, s50, v6
	v_mul_f32_e32 v2, v2, v0
	v_mul_f32_e32 v3, v3, v0
	v_mul_f32_e32 v4, v4, v0
	s_or_b64 s[6:7], vcc, s[6:7]
	v_mov_b32_e32 v28, v104
	v_mov_b32_e32 v29, v105
	v_mov_b32_e32 v30, v106
	v_mov_b32_e32 v31, v107
	v_mul_f32_e32 v7, v28, v7
	v_mul_f32_e32 v28, v29, v32
	v_mul_f32_e32 v29, v30, v33
	v_mul_f32_e32 v30, v31, v34
	s_nop 0
	v_cvt_pk_bf16_f32 v28, v7, v28
	s_nop 0
	v_cvt_pk_bf16_f32 v29, v29, v30
	global_store_dwordx2 v[60:61], v[28:29], off offset:512
	v_mul_f32_e32 v7, v36, v0
	v_mul_f32_e32 v32, v37, v0
	v_mul_f32_e32 v33, v38, v0
	v_mul_f32_e32 v34, v39, v0
	v_mov_b32_e32 v28, v108
	v_mov_b32_e32 v29, v109
	v_mov_b32_e32 v30, v110
	v_mov_b32_e32 v31, v111
	v_mul_f32_e32 v7, v28, v7
	v_mul_f32_e32 v28, v29, v32
	v_mul_f32_e32 v29, v30, v33
	v_mul_f32_e32 v30, v31, v34
	s_nop 0
	v_cvt_pk_bf16_f32 v28, v7, v28
	s_nop 0
	v_cvt_pk_bf16_f32 v29, v29, v30
	global_store_dwordx2 v[60:61], v[28:29], off offset:1024
	v_mul_f32_e32 v7, v40, v0
	v_mul_f32_e32 v32, v41, v0
	v_mul_f32_e32 v33, v42, v0
	v_mul_f32_e32 v34, v43, v0
	v_mov_b32_e32 v28, v112
	v_mov_b32_e32 v29, v113
	v_mov_b32_e32 v30, v114
	v_mov_b32_e32 v31, v115
	v_mul_f32_e32 v7, v7, v28
	v_mul_f32_e32 v28, v32, v29
	v_mul_f32_e32 v29, v33, v30
	v_mul_f32_e32 v30, v34, v31
	s_nop 0
	v_cvt_pk_bf16_f32 v28, v7, v28
	s_nop 0
	v_cvt_pk_bf16_f32 v29, v29, v30
	global_store_dwordx2 v[60:61], v[28:29], off offset:1536
	v_mul_f32_e32 v7, v44, v0
	v_mul_f32_e32 v32, v45, v0
	v_mul_f32_e32 v33, v46, v0
	v_mul_f32_e32 v34, v47, v0
	v_mov_b32_e32 v28, v116
	v_mov_b32_e32 v29, v117
	v_mov_b32_e32 v30, v118
	v_mov_b32_e32 v31, v119
	v_mul_f32_e32 v7, v7, v28
	v_mul_f32_e32 v28, v32, v29
	v_mul_f32_e32 v29, v33, v30
	v_mul_f32_e32 v30, v34, v31
	s_nop 0
	v_cvt_pk_bf16_f32 v28, v7, v28
	s_nop 0
	v_cvt_pk_bf16_f32 v29, v29, v30
	global_store_dwordx2 v[60:61], v[28:29], off offset:2048
	v_mul_f32_e32 v7, v48, v0
	v_mul_f32_e32 v32, v49, v0
	v_mul_f32_e32 v33, v50, v0
	v_mul_f32_e32 v34, v51, v0
	v_mov_b32_e32 v28, v120
	v_mov_b32_e32 v29, v121
	v_mov_b32_e32 v30, v122
	v_mov_b32_e32 v31, v123
	v_mul_f32_e32 v7, v7, v28
	v_mul_f32_e32 v28, v32, v29
	v_mul_f32_e32 v29, v33, v30
	v_mul_f32_e32 v30, v34, v31
	s_nop 0
	v_cvt_pk_bf16_f32 v28, v7, v28
	s_nop 0
	v_cvt_pk_bf16_f32 v29, v29, v30
	global_store_dwordx2 v[60:61], v[28:29], off offset:2560
	v_mul_f32_e32 v7, v52, v0
	v_mul_f32_e32 v32, v53, v0
	v_mul_f32_e32 v33, v54, v0
	v_mul_f32_e32 v34, v55, v0
	v_mul_f32_e32 v0, v5, v0
	v_mov_b32_e32 v28, v124
	v_mov_b32_e32 v29, v125
	v_mov_b32_e32 v30, v126
	v_mov_b32_e32 v31, v127
	v_mul_f32_e32 v7, v7, v28
	v_mul_f32_e32 v28, v32, v29
	v_mul_f32_e32 v29, v33, v30
	v_mul_f32_e32 v30, v34, v31
	s_nop 0
	v_cvt_pk_bf16_f32 v28, v7, v28
	s_nop 0
	v_cvt_pk_bf16_f32 v29, v29, v30
	global_store_dwordx2 v[60:61], v[28:29], off offset:3072
	v_mov_b32_e32 v28, v128
	v_mov_b32_e32 v29, v129
	v_mov_b32_e32 v30, v130
	v_mov_b32_e32 v31, v131
	v_mul_f32_e32 v2, v2, v28
	v_mul_f32_e32 v3, v3, v29
	v_mul_f32_e32 v4, v4, v30
	v_mul_f32_e32 v0, v0, v31
	s_nop 0
	v_cvt_pk_bf16_f32 v2, v2, v3
	s_nop 0
	v_cvt_pk_bf16_f32 v3, v4, v0
	global_store_dwordx2 v[60:61], v[2:3], off offset:3584
	s_andn2_b64 exec, exec, s[6:7]
	s_cbranch_execnz .LBB0_353

; __device__ __forceinline__ bf16_t f2bf(float f) { return (bf16_t)(cvt_pk_bf16(f, 0.f) & 0xffffu); }
; #define LDS_FENCE() asm volatile("s_waitcnt lgkmcnt(0)" ::: "memory")
; template <bool OUT>
; __device__ __forceinline__ void s5_item(KP P, int l, int item, int lane, LAS unsigned char* ldsw) {
;     ...
;     const float dt = expf(P->in[18][lg]);
;     float are, aim;
;     { const float lr = P->in[16][lg * 64 + lane], li = P->in[17][lg * 64 + lane]; const float mag = expf(lr * dt); float sn, cs; sincosf(li * dt, &sn, &cs); are = mag * cs; aim = mag * sn; }
;     ...
; #pragma unroll 1
;     for (int sub = 0; sub < 4; ++sub) {
;         const int tb = c * 64 + sub * 16;
;         u32x4 uw = {0u, 0u, 0u, 0u};
;         if (fq < 2) uw = *(const u32x4*)(proj + (size_t)(tb + fr) * NP + O_DU + g * 16 + fq * 8);
;         const bf16x8 ua = __builtin_bit_cast(bf16x8, uw);
; #pragma unroll
;         for (int ns = 0; ns < 8; ++ns) { const f32x4 z = {0.f, 0.f, 0.f, 0.f}; const f32x4 r = __builtin_amdgcn_mfma_f32_16x16x32_bf16(ua, bfr[ns], z, 0, 0, 0);
; #pragma unroll
;             for (int j = 0; j < 4; ++j) buL[(fq * 4 + j) * 132 + ns * 16 + fr] = r[j]; }
;         LDS_FENCE();
; #pragma unroll
;         for (int t = 0; t < 16; ++t) { const float br = buL[t * 132 + lane], bi = buL[t * 132 + 64 + lane];
;             const float nr = are * xr - aim * xi + br, ni = are * xi + aim * xr + bi; xr = nr; xi = ni;
;             if (OUT) { xL[t * 136 + lane] = f2bf(xr); xL[t * 136 + 64 + lane] = f2bf(xi); } }
.LBB0_570:
	s_or_b64 exec, exec, s[30:31]
	s_waitcnt vmcnt(0)
	v_mul_f32_e32 v0, v57, v58
	v_mul_f32_e32 v34, 0x3fb8aa3b, v0
	v_fma_f32 v35, v0, s86, -v34
	v_rndne_f32_e32 v36, v34
	v_fmac_f32_e32 v35, 0x32a5705f, v0
	v_sub_f32_e32 v34, v34, v36
	v_add_f32_e32 v34, v34, v35
	v_cvt_i32_f32_e32 v35, v36
	v_exp_f32_e32 v34, v34
	v_cmp_ngt_f32_e32 vcc, s91, v0
	v_and_b32_e32 v37, 1, v62
	v_xor_b32_e32 v38, v60, v59
	v_ldexp_f32 v34, v34, v35
	v_cndmask_b32_e32 v34, 0, v34, vcc
	v_cmp_nlt_f32_e32 vcc, s89, v0
	s_brev_b32 s4, 1
	v_mov_b32_e32 v52, 0
	v_cndmask_b32_e32 v0, v180, v34, vcc
	v_mul_f32_e32 v34, v61, v61
	v_fmamk_f32 v35, v34, 0xb94c1982, v244
	v_fmaak_f32 v35, v34, v35, 0xbe2aaa9d
	v_mul_f32_e32 v35, v34, v35
	v_fmac_f32_e32 v61, v61, v35
	v_fmamk_f32 v35, v34, 0x37d75334, v186
	v_fmaak_f32 v35, v34, v35, 0x3d2aabf7
	v_fmaak_f32 v35, v34, v35, 0xbf000004
	v_fma_f32 v34, v34, v35, 1.0
	v_cmp_eq_u32_e32 vcc, 0, v37
	v_lshlrev_b32_e32 v35, 30, v62
	v_and_b32_e32 v36, 0x80000000, v35
	v_cndmask_b32_e32 v37, v34, v61, vcc
	v_xor_b32_e32 v37, v38, v37
	v_xor_b32_e32 v36, v37, v36
	v_xor_b32_e32 v37, 0x80000000, v61
	v_cndmask_b32_e32 v34, v37, v34, vcc
	v_bitop3_b32 v34, v34, v35, s4 bitop3:0x78
	s_movk_i32 s4, 0x1f8
	v_cmp_class_f32_e64 vcc, v59, s4
	v_ashrrev_i32_e32 v38, 5, v49
	s_mov_b32 s30, 0
	v_cndmask_b32_e32 v34, v248, v34, vcc
	v_mul_f32_e32 v40, v0, v34
	v_cndmask_b32_e32 v34, v248, v36, vcc
	v_mul_f32_e32 v42, v0, v34
	v_lshlrev_b32_e32 v0, 4, v56
	v_mov_b32_e32 v41, v40
	v_mov_b32_e32 v43, v42
	v_mov_b32_e32 v44, v40
	v_mov_b32_e32 v45, v42
	v_mov_b32_e32 v46, v42
	v_mov_b32_e32 v47, v40
	v_lshl_or_b32 v39, v38, 6, v51
	v_lshlrev_b32_e32 v0, 1, v0
	v_mov_b32_e32 v53, v52
	v_mov_b32_e32 v100, 0
	v_mov_b32_e32 v101, 0
	v_mov_b32_e32 v102, 0
	v_mov_b32_e32 v103, 0
	s_and_saveexec_b64 s[20:21], s[42:43]
	s_cbranch_execz .Lmy_s5a_pf0
	v_add_u32_e32 v102, s30, v39
	v_mov_b64_e32 v[100:101], s[24:25]
	v_mad_i64_i32 v[100:101], s[44:45], v102, s26, v[100:101]
	v_lshl_add_u64 v[100:101], v[100:101], 0, v[0:1]
	v_lshlrev_b32_e32 v102, 1, v50
	v_mov_b32_e32 v103, v1
	v_lshl_add_u64 v[100:101], v[100:101], 0, v[102:103]
	v_add_co_u32_e32 v100, vcc, 0x17b04000, v100
	s_nop 1
	v_addc_co_u32_e32 v101, vcc, 0, v101, vcc
	global_load_dwordx4 v[100:103], v[100:101], off offset:272
.Lmy_s5a_pf0:
	s_or_b64 exec, exec, s[20:21]
	s_branch .LBB0_572
.LBB0_571:
	v_mfma_f32_16x16x32_bf16 v[58:61], v[34:37], v[2:5], 0
	v_add_u32_e32 v57, 0x400, v55
	s_add_i32 s30, s30, 16
	s_cmp_lg_u32 s30, 64
	v_mfma_f32_16x16x32_bf16 v[62:65], v[34:37], v[10:13], 0
	s_nop 7
	ds_write2_b32 v55, v58, v62 offset1:16
	ds_write2_b32 v55, v59, v63 offset0:132 offset1:148
	ds_write2_b32 v57, v60, v64 offset0:8 offset1:24
	ds_write2_b32 v57, v61, v65 offset0:140 offset1:156
	v_mfma_f32_16x16x32_bf16 v[58:61], v[34:37], v[18:21], 0
	v_mfma_f32_16x16x32_bf16 v[62:65], v[34:37], v[26:29], 0
	s_nop 7
	ds_write2_b32 v55, v58, v62 offset0:32 offset1:48
	ds_write2_b32 v55, v59, v63 offset0:164 offset1:180
	ds_write2_b32 v57, v60, v64 offset0:40 offset1:56
	ds_write2_b32 v57, v61, v65 offset0:172 offset1:188
	v_mfma_f32_16x16x32_bf16 v[58:61], v[34:37], v[6:9], 0
	v_mfma_f32_16x16x32_bf16 v[62:65], v[34:37], v[14:17], 0
	s_nop 7
	ds_write2_b32 v55, v58, v62 offset0:64 offset1:80
	ds_write2_b32 v55, v59, v63 offset0:196 offset1:212
	ds_write2_b32 v57, v60, v64 offset0:72 offset1:88
	ds_write2_b32 v57, v61, v65 offset0:204 offset1:220
	v_mfma_f32_16x16x32_bf16 v[58:61], v[34:37], v[22:25], 0
	v_mfma_f32_16x16x32_bf16 v[34:37], v[34:37], v[30:33], 0
	s_nop 7
	ds_write2_b32 v55, v58, v34 offset0:96 offset1:112
	ds_write2_b32 v55, v59, v35 offset0:228 offset1:244
	ds_write2_b32 v57, v60, v36 offset0:104 offset1:120
	ds_write2_b32 v57, v61, v37 offset0:236 offset1:252
	s_waitcnt lgkmcnt(0)
	ds_read2st64_b32 v[34:35], v54 offset1:1
	v_pk_mul_f32 v[36:37], v[40:41], v[52:53]
	ds_read2_b32 v[58:59], v54 offset0:132 offset1:196
	v_pk_fma_f32 v[60:61], v[42:43], v[52:53], v[36:37] op_sel:[0,0,1] op_sel_hi:[1,1,0]
	v_pk_fma_f32 v[36:37], v[42:43], v[52:53], v[36:37] op_sel:[0,0,1] op_sel_hi:[1,1,0] neg_lo:[1,0,0] neg_hi:[1,0,0]
	v_add_u32_e32 v57, 64, v54
	v_mov_b32_e32 v61, v37
	s_waitcnt lgkmcnt(1)
	v_mov_b32_e32 v36, v35
	v_mov_b32_e32 v37, v34
	v_pk_add_f32 v[34:35], v[60:61], v[36:37]
	s_waitcnt lgkmcnt(0)
	v_mov_b32_e32 v64, v59
	v_pk_mul_f32 v[36:37], v[42:43], v[34:35]
	v_mov_b32_e32 v65, v58
	v_pk_fma_f32 v[52:53], v[40:41], v[34:35], v[36:37] op_sel:[0,0,1] op_sel_hi:[1,1,0]
	v_pk_fma_f32 v[34:35], v[40:41], v[34:35], v[36:37] op_sel:[0,0,1] op_sel_hi:[1,1,0] neg_lo:[0,0,1] neg_hi:[0,0,1]
	v_add_u32_e32 v36, 48, v54
	v_add_u32_e32 v34, 32, v54
	v_mov_b32_e32 v53, v35
	ds_read2st64_b32 v[34:35], v34 offset0:4 offset1:5
	v_pk_add_f32 v[52:53], v[64:65], v[52:53]
	ds_read2st64_b32 v[36:37], v36 offset0:6 offset1:7
	v_pk_mul_f32 v[58:59], v[42:43], v[52:53]
	ds_read2st64_b32 v[60:61], v57 offset0:8 offset1:9
	v_pk_fma_f32 v[64:65], v[40:41], v[52:53], v[58:59] op_sel:[0,0,1] op_sel_hi:[1,1,0]
	v_pk_fma_f32 v[52:53], v[40:41], v[52:53], v[58:59] op_sel:[0,0,1] op_sel_hi:[1,1,0] neg_lo:[0,0,1] neg_hi:[0,0,1]
	v_add_u32_e32 v57, 0x50, v54
	v_mov_b32_e32 v65, v53
	s_waitcnt lgkmcnt(2)
	v_mov_b32_e32 v52, v35
	v_mov_b32_e32 v53, v34
	v_pk_add_f32 v[34:35], v[52:53], v[64:65]
	ds_read2st64_b32 v[62:63], v57 offset0:10 offset1:11
	v_pk_mul_f32 v[52:53], v[42:43], v[34:35]
	v_add_u32_e32 v57, 0xb0, v54
	v_pk_fma_f32 v[58:59], v[40:41], v[34:35], v[52:53] op_sel:[0,0,1] op_sel_hi:[1,1,0]
	v_pk_fma_f32 v[34:35], v[40:41], v[34:35], v[52:53] op_sel:[0,0,1] op_sel_hi:[1,1,0] neg_lo:[0,0,1] neg_hi:[0,0,1]
	s_nop 0
	v_mov_b32_e32 v59, v35
	s_waitcnt lgkmcnt(2)
; __device__ __forceinline__ bf16_t f2bf(float f) { return (bf16_t)(cvt_pk_bf16(f, 0.f) & 0xffffu); }
; template <bool OUT>
; __device__ __forceinline__ void s5_item(KP P, int l, int item, int lane, LAS unsigned char* ldsw) {
;     ...
;         const int tb = c * 64 + sub * 16;
;         u32x4 uw = {0u, 0u, 0u, 0u};
;         if (fq < 2) uw = *(const u32x4*)(proj + (size_t)(tb + fr) * NP + O_DU + g * 16 + fq * 8);
;         const bf16x8 ua = __builtin_bit_cast(bf16x8, uw);
;     ...
; #pragma unroll
;         for (int t = 0; t < 16; ++t) { const float br = buL[t * 132 + lane], bi = buL[t * 132 + 64 + lane];
;             const float nr = are * xr - aim * xi + br, ni = are * xi + aim * xr + bi; xr = nr; xi = ni;
;             if (OUT) { xL[t * 136 + lane] = f2bf(xr); xL[t * 136 + 64 + lane] = f2bf(xi); } }
	v_mov_b32_e32 v34, v37
	v_mov_b32_e32 v35, v36
	v_pk_add_f32 v[34:35], v[34:35], v[58:59]
	s_nop 0
	v_pk_mul_f32 v[36:37], v[42:43], v[34:35]
	s_nop 0
	v_pk_fma_f32 v[52:53], v[40:41], v[34:35], v[36:37] op_sel:[0,0,1] op_sel_hi:[1,1,0]
	v_pk_fma_f32 v[34:35], v[40:41], v[34:35], v[36:37] op_sel:[0,0,1] op_sel_hi:[1,1,0] neg_lo:[0,0,1] neg_hi:[0,0,1]
	s_nop 0
	v_mov_b32_e32 v53, v35
	s_waitcnt lgkmcnt(1)
	v_mov_b32_e32 v34, v61
	v_mov_b32_e32 v35, v60
	v_pk_add_f32 v[34:35], v[34:35], v[52:53]
	s_nop 0
	v_mul_f32_e32 v36, v47, v35
	v_mul_f32_e32 v52, v44, v34
	v_pk_fma_f32 v[36:37], v[46:47], v[34:35], v[36:37] op_sel_hi:[1,1,0] neg_lo:[1,0,0] neg_hi:[1,0,0]
	v_pk_fma_f32 v[34:35], v[44:45], v[34:35], v[52:53] op_sel_hi:[1,1,0]
	s_nop 0
	v_add_u32_e32 v34, 0x60, v54
	ds_read2st64_b32 v[52:53], v34 offset0:12 offset1:13
	v_add_u32_e32 v34, 0x70, v54
	ds_read2st64_b32 v[58:59], v34 offset0:14 offset1:15
	v_add_u32_e32 v34, 0x80, v54
	v_mov_b32_e32 v37, v35
	ds_read2st64_b32 v[60:61], v34 offset0:16 offset1:17
	s_waitcnt lgkmcnt(3)
	v_pk_add_f32 v[34:35], v[62:63], v[36:37]
	s_nop 0
	v_pk_mul_f32 v[36:37], v[42:43], v[34:35]
	s_nop 0
	v_pk_fma_f32 v[62:63], v[40:41], v[34:35], v[36:37] op_sel:[0,0,1] op_sel_hi:[1,1,0] neg_lo:[0,0,1] neg_hi:[0,0,1]
	v_pk_fma_f32 v[34:35], v[40:41], v[34:35], v[36:37] op_sel:[0,0,1] op_sel_hi:[1,1,0]
	s_nop 0
	v_mov_b32_e32 v63, v35
	s_waitcnt lgkmcnt(2)
	v_pk_add_f32 v[34:35], v[52:53], v[62:63]
	s_nop 0
	v_pk_mul_f32 v[36:37], v[42:43], v[34:35]
	s_nop 0
	v_pk_fma_f32 v[52:53], v[40:41], v[34:35], v[36:37] op_sel:[0,0,1] op_sel_hi:[1,1,0] neg_lo:[0,0,1] neg_hi:[0,0,1]
	v_pk_fma_f32 v[34:35], v[40:41], v[34:35], v[36:37] op_sel:[0,0,1] op_sel_hi:[1,1,0]
	s_nop 0
	v_mov_b32_e32 v53, v35
	s_waitcnt lgkmcnt(1)
	v_pk_add_f32 v[34:35], v[58:59], v[52:53]
	ds_read2st64_b32 v[58:59], v57 offset0:22 offset1:23
	v_pk_mul_f32 v[36:37], v[42:43], v[34:35]
	v_add_u32_e32 v57, 0xc0, v54
	v_pk_fma_f32 v[52:53], v[40:41], v[34:35], v[36:37] op_sel:[0,0,1] op_sel_hi:[1,1,0] neg_lo:[0,0,1] neg_hi:[0,0,1]
	v_pk_fma_f32 v[34:35], v[40:41], v[34:35], v[36:37] op_sel:[0,0,1] op_sel_hi:[1,1,0]
	v_add_u32_e32 v36, 0x90, v54
	v_mov_b32_e32 v53, v35
	ds_read2st64_b32 v[36:37], v36 offset0:18 offset1:19
	s_waitcnt lgkmcnt(2)
	v_pk_add_f32 v[34:35], v[60:61], v[52:53]
	v_add_u32_e32 v52, 0xa0, v54
	v_pk_mul_f32 v[62:63], v[42:43], v[34:35]
	ds_read2st64_b32 v[52:53], v52 offset0:20 offset1:21
	v_pk_fma_f32 v[64:65], v[40:41], v[34:35], v[62:63] op_sel:[0,0,1] op_sel_hi:[1,1,0] neg_lo:[0,0,1] neg_hi:[0,0,1]
	v_pk_fma_f32 v[34:35], v[40:41], v[34:35], v[62:63] op_sel:[0,0,1] op_sel_hi:[1,1,0]
	ds_read2st64_b32 v[60:61], v57 offset0:24 offset1:25
	v_mov_b32_e32 v65, v35
	s_waitcnt lgkmcnt(2)
	v_pk_add_f32 v[34:35], v[36:37], v[64:65]
	v_add_u32_e32 v57, 0xf0, v54
	v_pk_mul_f32 v[36:37], v[42:43], v[34:35]
	s_nop 0
	v_pk_fma_f32 v[62:63], v[40:41], v[34:35], v[36:37] op_sel:[0,0,1] op_sel_hi:[1,1,0] neg_lo:[0,0,1] neg_hi:[0,0,1]
	v_pk_fma_f32 v[34:35], v[40:41], v[34:35], v[36:37] op_sel:[0,0,1] op_sel_hi:[1,1,0]
	s_nop 0
	v_mov_b32_e32 v63, v35
	s_waitcnt lgkmcnt(1)
	v_pk_add_f32 v[34:35], v[52:53], v[62:63]
	s_nop 0
	v_pk_mul_f32 v[36:37], v[42:43], v[34:35]
	s_nop 0
	v_pk_fma_f32 v[52:53], v[40:41], v[34:35], v[36:37] op_sel:[0,0,1] op_sel_hi:[1,1,0] neg_lo:[0,0,1] neg_hi:[0,0,1]
	v_pk_fma_f32 v[34:35], v[40:41], v[34:35], v[36:37] op_sel:[0,0,1] op_sel_hi:[1,1,0]
	s_nop 0
	v_mov_b32_e32 v53, v35
	v_pk_add_f32 v[34:35], v[58:59], v[52:53]
	ds_read2st64_b32 v[58:59], v57 offset0:30 offset1:31
	v_pk_mul_f32 v[36:37], v[42:43], v[34:35]
	s_nop 0
	v_pk_fma_f32 v[52:53], v[40:41], v[34:35], v[36:37] op_sel:[0,0,1] op_sel_hi:[1,1,0] neg_lo:[0,0,1] neg_hi:[0,0,1]
	v_pk_fma_f32 v[34:35], v[40:41], v[34:35], v[36:37] op_sel:[0,0,1] op_sel_hi:[1,1,0]
	v_add_u32_e32 v36, 0xe0, v54
	v_add_u32_e32 v34, 0xd0, v54
	v_mov_b32_e32 v53, v35
	ds_read2st64_b32 v[34:35], v34 offset0:26 offset1:27
	s_waitcnt lgkmcnt(2)
	v_pk_add_f32 v[52:53], v[60:61], v[52:53]
	ds_read2st64_b32 v[36:37], v36 offset0:28 offset1:29
	v_pk_mul_f32 v[60:61], v[42:43], v[52:53]
	s_waitcnt lgkmcnt(0)
	s_nop 0
	v_pk_fma_f32 v[62:63], v[40:41], v[52:53], v[60:61] op_sel:[0,0,1] op_sel_hi:[1,1,0] neg_lo:[0,0,1] neg_hi:[0,0,1]
	v_pk_fma_f32 v[52:53], v[40:41], v[52:53], v[60:61] op_sel:[0,0,1] op_sel_hi:[1,1,0]
	s_nop 0
	v_mov_b32_e32 v63, v53
	s_waitcnt lgkmcnt(1)
	v_pk_add_f32 v[34:35], v[34:35], v[62:63]
	s_nop 0
	v_pk_mul_f32 v[52:53], v[42:43], v[34:35]
	s_nop 0
	v_pk_fma_f32 v[60:61], v[40:41], v[34:35], v[52:53] op_sel:[0,0,1] op_sel_hi:[1,1,0] neg_lo:[0,0,1] neg_hi:[0,0,1]
	v_pk_fma_f32 v[34:35], v[40:41], v[34:35], v[52:53] op_sel:[0,0,1] op_sel_hi:[1,1,0]
	s_nop 0
	v_mov_b32_e32 v61, v35
	s_waitcnt lgkmcnt(0)
	v_pk_add_f32 v[34:35], v[36:37], v[60:61]
	s_nop 0
	v_pk_mul_f32 v[36:37], v[42:43], v[34:35]
	s_nop 0
	v_pk_fma_f32 v[52:53], v[40:41], v[34:35], v[36:37] op_sel:[0,0,1] op_sel_hi:[1,1,0] neg_lo:[0,0,1] neg_hi:[0,0,1]
	v_pk_fma_f32 v[34:35], v[40:41], v[34:35], v[36:37] op_sel:[0,0,1] op_sel_hi:[1,1,0]
	s_nop 0
	v_mov_b32_e32 v53, v35
	v_pk_add_f32 v[52:53], v[58:59], v[52:53]
	s_cbranch_scc0 .LBB0_541
.LBB0_572:
	s_waitcnt vmcnt(0)
	v_mov_b32_e32 v34, v100
	v_mov_b32_e32 v35, v101
	v_mov_b32_e32 v36, v102
	v_mov_b32_e32 v37, v103
	s_cmp_eq_u32 s30, 48
	s_cbranch_scc1 .Lmy_s5a_nopf
	v_mov_b32_e32 v100, 0
	v_mov_b32_e32 v101, 0
	v_mov_b32_e32 v102, 0
	v_mov_b32_e32 v103, 0
	s_and_saveexec_b64 s[20:21], s[42:43]
	s_cbranch_execz .Lmy_s5a_pf1
	v_add3_u32 v102, s30, v39, 16
	v_mov_b64_e32 v[100:101], s[24:25]
	v_mad_i64_i32 v[100:101], s[44:45], v102, s26, v[100:101]
	v_lshl_add_u64 v[100:101], v[100:101], 0, v[0:1]
	v_lshlrev_b32_e32 v102, 1, v50
	v_mov_b32_e32 v103, v1
	v_lshl_add_u64 v[100:101], v[100:101], 0, v[102:103]
	v_add_co_u32_e32 v100, vcc, 0x17b04000, v100
	s_nop 1
	v_addc_co_u32_e32 v101, vcc, 0, v101, vcc
	global_load_dwordx4 v[100:103], v[100:101], off offset:272

; template <bool OUT>
; __device__ __forceinline__ void s5_item(KP P, int l, int item, int lane, LAS unsigned char* ldsw) {
;     ...
;         const int tb = c * 64 + sub * 16;
;         u32x4 uw = {0u, 0u, 0u, 0u};
;         if (fq < 2) uw = *(const u32x4*)(proj + (size_t)(tb + fr) * NP + O_DU + g * 16 + fq * 8);
;         const bf16x8 ua = __builtin_bit_cast(bf16x8, uw);
.Lmy_s5a_nopf:
	s_nop 1
	s_branch .LBB0_571

; __device__ __forceinline__ unsigned pack_bf2(float a, float b) { return cvt_pk_bf16(a, b); }
; template <bool OUT>
; __device__ __forceinline__ void s5_item(KP P, int l, int item, int lane, LAS unsigned char* ldsw) {
;     ...
;     bf16x8 cfr[4]; float dsk = 0.f;
;     if (OUT) {
; #pragma unroll
;         for (int ks = 0; ks < 4; ++ks) { const float* src = (ks < 2 ? P->in[21] : P->in[22]) + ((size_t)lg * 16 + fr) * 64 + (ks & 1) * 32 + fq * 8; const float sg = ks < 2 ? 1.f : -1.f;
;             const f32x4 a = *(const f32x4*)src, b = *(const f32x4*)(src + 4);
;             u32x4 w; w.x = pack_bf2(sg * a[0], sg * a[1]); w.y = pack_bf2(sg * a[2], sg * a[3]); w.z = pack_bf2(sg * b[0], sg * b[1]); w.w = pack_bf2(sg * b[2], sg * b[3]);
;             cfr[ks] = __builtin_bit_cast(bf16x8, w); }
;         dsk = P->in[23][l * 512 + g * 16 + fr];
;     }
;     float xr = 0.f, xi = 0.f;
;     if (OUT) { const float* xs = (const float*)(P->ws + W_XST) + ((size_t)c * 2048 + g * 64 + lane) * 2; xr = xs[0]; xi = xs[1]; }
.LBB0_1102:
	s_or_b64 exec, exec, s[30:31]
	s_load_dwordx4 s[44:47], s[0:1], 0xa8
	v_lshlrev_b64 v[46:47], 12, v[0:1]
	v_mov_b32_e32 v63, v1
	v_lshlrev_b32_e32 v0, 2, v58
	v_ashrrev_i32_e32 v74, 5, v55
	s_waitcnt lgkmcnt(0)
	v_lshl_add_u64 v[34:35], s[44:45], 0, v[46:47]
	v_lshl_add_u64 v[34:35], v[34:35], 0, v[62:63]
	v_lshl_add_u64 v[42:43], v[34:35], 0, v[0:1]
	global_load_dwordx4 v[34:37], v[42:43], off
	global_load_dwordx4 v[38:41], v[42:43], off offset:16
	s_load_dwordx2 s[20:21], s[0:1], 0xb8
	v_lshl_add_u64 v[46:47], s[46:47], 0, v[46:47]
	v_lshl_add_u64 v[46:47], v[46:47], 0, v[62:63]
	v_lshl_add_u64 v[70:71], v[46:47], 0, v[0:1]
	v_ashrrev_i32_e32 v75, 31, v74
	v_lshlrev_b64 v[76:77], 11, v[74:75]
	v_lshlrev_b32_e32 v64, 4, v50
	v_xor_b32_e32 v66, v66, v53
	s_brev_b32 s4, 1
	s_mov_b32 s30, 0
	s_waitcnt vmcnt(1)
	s_nop 0
	v_cvt_pk_bf16_f32 v34, v34, v35
	s_nop 0
	v_cvt_pk_bf16_f32 v35, v36, v37
	s_waitcnt vmcnt(0)
	s_nop 0
	v_cvt_pk_bf16_f32 v36, v38, v39
	s_nop 0
	v_cvt_pk_bf16_f32 v37, v40, v41
	global_load_dwordx4 v[38:41], v[42:43], off offset:128
	s_nop 0
	global_load_dwordx4 v[42:45], v[42:43], off offset:144
	s_waitcnt vmcnt(1)
	s_nop 0
	v_cvt_pk_bf16_f32 v38, v38, v39
	s_nop 0
	v_cvt_pk_bf16_f32 v39, v40, v41
	s_waitcnt vmcnt(0)
	s_nop 0
	v_cvt_pk_bf16_f32 v40, v42, v43
	s_nop 0
	v_cvt_pk_bf16_f32 v41, v44, v45
	global_load_dwordx4 v[42:45], v[70:71], off
	global_load_dwordx4 v[46:49], v[70:71], off offset:16
	s_waitcnt vmcnt(1)
	v_xor_b32_e32 v0, 0x80000000, v42
	v_xor_b32_e32 v42, 0x80000000, v43
	v_xor_b32_e32 v43, 0x80000000, v44
	v_xor_b32_e32 v44, 0x80000000, v45
	s_waitcnt vmcnt(0)
	v_xor_b32_e32 v45, 0x80000000, v46
	v_xor_b32_e32 v46, 0x80000000, v47
	v_xor_b32_e32 v47, 0x80000000, v48
	v_xor_b32_e32 v48, 0x80000000, v49
	s_nop 0
	v_cvt_pk_bf16_f32 v42, v0, v42
	s_nop 0
	v_cvt_pk_bf16_f32 v43, v43, v44
	s_nop 0
	v_cvt_pk_bf16_f32 v44, v45, v46
	s_nop 0
	v_cvt_pk_bf16_f32 v45, v47, v48
	global_load_dwordx4 v[46:49], v[70:71], off offset:128
	s_nop 0
	global_load_dwordx4 v[70:73], v[70:71], off offset:144
	v_lshl_or_b32 v0, v50, 6, v76
	v_or_b32_e32 v76, v0, v54
	v_or_b32_e32 v0, v64, v57
	s_waitcnt lgkmcnt(0)
	v_lshl_add_u64 v[78:79], v[0:1], 2, s[20:21]
	v_lshl_add_u64 v[76:77], v[76:77], 3, s[34:35]
	s_waitcnt vmcnt(1)
	v_xor_b32_e32 v0, 0x80000000, v46
	v_xor_b32_e32 v46, 0x80000000, v47
	v_xor_b32_e32 v47, 0x80000000, v48
	v_xor_b32_e32 v48, 0x80000000, v49
	s_waitcnt vmcnt(0)
	v_xor_b32_e32 v49, 0x80000000, v70
	v_xor_b32_e32 v63, 0x80000000, v71
	v_xor_b32_e32 v69, 0x80000000, v72
	v_xor_b32_e32 v70, 0x80000000, v73
	s_nop 0
	v_cvt_pk_bf16_f32 v46, v0, v46
	s_nop 0
	v_cvt_pk_bf16_f32 v47, v47, v48
	s_nop 0
	v_cvt_pk_bf16_f32 v48, v49, v63
	s_nop 0
	v_cvt_pk_bf16_f32 v49, v69, v70
	global_load_dword v63, v[78:79], off
	global_load_dwordx2 v[72:73], v[76:77], off
	v_mul_f32_e32 v0, v51, v52
	v_mul_f32_e32 v51, 0x3fb8aa3b, v0
	v_fma_f32 v52, v0, s86, -v51
	v_rndne_f32_e32 v69, v51
	v_fmac_f32_e32 v52, 0x32a5705f, v0
	v_sub_f32_e32 v51, v51, v69
	v_add_f32_e32 v51, v51, v52
	v_exp_f32_e32 v51, v51
	v_cvt_i32_f32_e32 v52, v69
	v_cmp_ngt_f32_e32 vcc, s91, v0
	v_ldexp_f32 v51, v51, v52
	s_nop 0
	v_cndmask_b32_e32 v51, 0, v51, vcc
	v_cmp_nlt_f32_e32 vcc, s89, v0
	s_nop 1
	v_cndmask_b32_e32 v0, v180, v51, vcc
	v_mul_f32_e32 v51, v67, v67
	v_fmamk_f32 v52, v51, 0xb94c1982, v244
	v_fmaak_f32 v52, v51, v52, 0xbe2aaa9d
	v_mul_f32_e32 v52, v51, v52
	v_fmac_f32_e32 v67, v67, v52
	v_fmamk_f32 v52, v51, 0x37d75334, v186
	v_fmaak_f32 v52, v51, v52, 0x3d2aabf7
	v_fmaak_f32 v52, v51, v52, 0xbf000004
	v_fma_f32 v51, v51, v52, 1.0
	v_lshlrev_b32_e32 v52, 30, v68
	v_and_b32_e32 v68, 1, v68
	v_cmp_eq_u32_e32 vcc, 0, v68
	v_and_b32_e32 v69, 0x80000000, v52
	s_nop 0
	v_cndmask_b32_e32 v68, v51, v67, vcc
	v_xor_b32_e32 v66, v66, v68
	v_xor_b32_e32 v68, v66, v69
	v_xor_b32_e32 v66, 0x80000000, v67
	v_cndmask_b32_e32 v51, v66, v51, vcc
	v_bitop3_b32 v51, v51, v52, s4 bitop3:0x78
	s_movk_i32 s4, 0x1f8
	v_cmp_class_f32_e64 vcc, v53, s4
	s_nop 1
	v_cndmask_b32_e32 v51, v248, v51, vcc
	v_mul_f32_e32 v66, v0, v51
	v_cndmask_b32_e32 v51, v248, v68, vcc
	v_mul_f32_e32 v68, v0, v51
	v_lshlrev_b32_e32 v51, 6, v74
	v_lshlrev_b32_e32 v0, 5, v50
	v_lshl_add_u64 v[70:71], v[60:61], 0, v[0:1]
	v_mov_b32_e32 v67, v66
	v_mov_b32_e32 v69, v68
	v_or_b32_e32 v83, v59, v51
	v_or_b32_e32 v84, v56, v51
	v_mov_b32_e32 v100, 0
	v_mov_b32_e32 v101, 0
	v_mov_b32_e32 v102, 0
	v_mov_b32_e32 v103, 0
	s_and_saveexec_b64 s[20:21], s[42:43]
	s_cbranch_execz .Lmy_s5b_pf0
	v_lshlrev_b32_e32 v104, 1, v64
	v_mov_b32_e32 v105, v1
	v_add_u32_e32 v102, s30, v84
	v_mov_b64_e32 v[100:101], s[24:25]
	v_mad_i64_i32 v[100:101], s[44:45], v102, s26, v[100:101]
	v_lshl_add_u64 v[100:101], v[100:101], 0, v[104:105]
	v_lshlrev_b32_e32 v102, 1, v58
	v_mov_b32_e32 v103, v1
	v_lshl_add_u64 v[100:101], v[100:101], 0, v[102:103]
	v_add_co_u32_e32 v100, vcc, 0x4000, v100
	s_nop 1
	v_addc_co_u32_e32 v101, vcc, 0, v101, vcc
	global_load_dwordx4 v[100:103], v[100:101], off offset:272
.Lmy_s5b_pf0:
	s_or_b64 exec, exec, s[20:21]
	s_waitcnt vmcnt(0)
	s_branch .LBB0_1104
; __device__ __forceinline__ bf16_t f2bf(float f) { return (bf16_t)(cvt_pk_bf16(f, 0.f) & 0xffffu); }
; #define LDS_FENCE() asm volatile("s_waitcnt lgkmcnt(0)" ::: "memory")
; template <bool OUT>
; __device__ __forceinline__ void s5_item(KP P, int l, int item, int lane, LAS unsigned char* ldsw) {
;     ...
; #pragma unroll
;         for (int ns = 0; ns < 8; ++ns) { const f32x4 z = {0.f, 0.f, 0.f, 0.f}; const f32x4 r = __builtin_amdgcn_mfma_f32_16x16x32_bf16(ua, bfr[ns], z, 0, 0, 0);
; #pragma unroll
;             for (int j = 0; j < 4; ++j) buL[(fq * 4 + j) * 132 + ns * 16 + fr] = r[j]; }
;         LDS_FENCE();
; #pragma unroll
;         for (int t = 0; t < 16; ++t) { const float br = buL[t * 132 + lane], bi = buL[t * 132 + 64 + lane];
;             const float nr = are * xr - aim * xi + br, ni = are * xi + aim * xr + bi; xr = nr; xi = ni;
;             if (OUT) { xL[t * 136 + lane] = f2bf(xr); xL[t * 136 + 64 + lane] = f2bf(xi); } }
.LBB0_1103:
	v_mfma_f32_16x16x32_bf16 v[74:77], v[50:53], v[2:5], 0
	v_add_u32_e32 v78, 0x400, v80
	v_mfma_f32_16x16x32_bf16 v[86:89], v[50:53], v[10:13], 0
	s_nop 7
	ds_write2_b32 v80, v74, v86 offset1:16
	ds_write2_b32 v80, v75, v87 offset0:132 offset1:148
	ds_write2_b32 v78, v76, v88 offset0:8 offset1:24
	ds_write2_b32 v78, v77, v89 offset0:140 offset1:156
	v_mfma_f32_16x16x32_bf16 v[74:77], v[50:53], v[18:21], 0
	v_mfma_f32_16x16x32_bf16 v[86:89], v[50:53], v[26:29], 0
	s_nop 7
	ds_write2_b32 v80, v74, v86 offset0:32 offset1:48
	ds_write2_b32 v80, v75, v87 offset0:164 offset1:180
	ds_write2_b32 v78, v76, v88 offset0:40 offset1:56
	ds_write2_b32 v78, v77, v89 offset0:172 offset1:188
	v_mfma_f32_16x16x32_bf16 v[74:77], v[50:53], v[6:9], 0
	v_mfma_f32_16x16x32_bf16 v[86:89], v[50:53], v[14:17], 0
	s_nop 7
	ds_write2_b32 v80, v74, v86 offset0:64 offset1:80
	ds_write2_b32 v80, v75, v87 offset0:196 offset1:212
	ds_write2_b32 v78, v76, v88 offset0:72 offset1:88
	ds_write2_b32 v78, v77, v89 offset0:204 offset1:220
	v_mfma_f32_16x16x32_bf16 v[74:77], v[50:53], v[22:25], 0
	v_mfma_f32_16x16x32_bf16 v[50:53], v[50:53], v[30:33], 0
	s_nop 7
	ds_write2_b32 v80, v74, v50 offset0:96 offset1:112
	ds_write2_b32 v80, v75, v51 offset0:228 offset1:244
	ds_write2_b32 v78, v76, v52 offset0:104 offset1:120
	ds_write2_b32 v78, v77, v53 offset0:236 offset1:252
	s_waitcnt lgkmcnt(0)
	ds_read2st64_b32 v[50:51], v65 offset1:1
	v_mul_f32_e32 v52, v68, v73
	v_fma_f32 v52, v66, v72, -v52
	v_add_u32_e32 v78, s30, v83
	v_ashrrev_i32_e32 v79, 31, v78
	s_waitcnt lgkmcnt(0)
	v_add_f32_e32 v52, v52, v50
	v_mul_f32_e32 v50, v66, v73
	v_fmac_f32_e32 v50, v68, v72
	v_add_f32_e32 v53, v50, v51
	s_nop 0
	v_cvt_pk_bf16_f32 v50, v52, v1
	ds_write_b16 v82, v50 offset:8448
	s_nop 0
	v_cvt_pk_bf16_f32 v50, v53, v1
	ds_write_b16 v82, v50 offset:8576
	ds_read2_b32 v[50:51], v65 offset0:132 offset1:196
	v_mul_f32_e32 v72, v68, v53
	v_fma_f32 v72, v66, v52, -v72
	s_add_i32 s30, s30, 16
	s_cmp_lg_u32 s30, 64
	s_waitcnt lgkmcnt(0)
	v_add_f32_e32 v72, v72, v50
	v_mul_f32_e32 v50, v66, v53
	v_fmac_f32_e32 v50, v68, v52
	v_add_f32_e32 v52, v50, v51
	s_nop 0
	v_cvt_pk_bf16_f32 v50, v72, v1
	ds_write_b16 v82, v50 offset:8720
	s_nop 0
	v_cvt_pk_bf16_f32 v50, v52, v1
	ds_write_b16 v82, v50 offset:8848
	v_add_u32_e32 v50, 32, v65
	ds_read2st64_b32 v[50:51], v50 offset0:4 offset1:5
	v_mul_f32_e32 v53, v68, v52
	v_fma_f32 v53, v66, v72, -v53
	s_waitcnt lgkmcnt(0)
	v_add_f32_e32 v53, v53, v50
	v_mul_f32_e32 v50, v66, v52
	v_fmac_f32_e32 v50, v68, v72
	v_add_f32_e32 v52, v50, v51
	s_nop 0
	v_cvt_pk_bf16_f32 v50, v53, v1
	ds_write_b16 v82, v50 offset:8992
	s_nop 0
	v_cvt_pk_bf16_f32 v50, v52, v1
	ds_write_b16 v82, v50 offset:9120
	v_add_u32_e32 v50, 48, v65
	ds_read2st64_b32 v[50:51], v50 offset0:6 offset1:7
	v_mul_f32_e32 v72, v68, v52
	v_fma_f32 v72, v66, v53, -v72
	s_waitcnt lgkmcnt(0)
	v_add_f32_e32 v72, v72, v50
	v_mul_f32_e32 v50, v66, v52
	v_fmac_f32_e32 v50, v68, v53
	v_add_f32_e32 v52, v50, v51
	s_nop 0
	v_cvt_pk_bf16_f32 v50, v72, v1
	ds_write_b16 v82, v50 offset:9264
	s_nop 0
	v_cvt_pk_bf16_f32 v50, v52, v1
	ds_write_b16 v82, v50 offset:9392
	v_add_u32_e32 v50, 64, v65
	ds_read2st64_b32 v[50:51], v50 offset0:8 offset1:9
	v_mul_f32_e32 v53, v68, v52
	v_fma_f32 v53, v66, v72, -v53
	s_waitcnt lgkmcnt(0)
	v_add_f32_e32 v53, v53, v50
	v_mul_f32_e32 v50, v66, v52
	v_fmac_f32_e32 v50, v68, v72
	v_add_f32_e32 v52, v50, v51
	s_nop 0
	v_cvt_pk_bf16_f32 v50, v53, v1
	ds_write_b16 v82, v50 offset:9536
	s_nop 0
	v_cvt_pk_bf16_f32 v50, v52, v1
	ds_write_b16 v82, v50 offset:9664
	v_add_u32_e32 v50, 0x50, v65
	ds_read2st64_b32 v[50:51], v50 offset0:10 offset1:11
	v_mul_f32_e32 v72, v68, v52
	v_fma_f32 v72, v66, v53, -v72
	s_waitcnt lgkmcnt(0)
	v_add_f32_e32 v72, v72, v50
	v_mul_f32_e32 v50, v66, v52
	v_fmac_f32_e32 v50, v68, v53
	v_add_f32_e32 v52, v50, v51
	s_nop 0
	v_cvt_pk_bf16_f32 v50, v72, v1
	ds_write_b16 v82, v50 offset:9808
	s_nop 0
	v_cvt_pk_bf16_f32 v50, v52, v1
	ds_write_b16 v82, v50 offset:9936
	v_add_u32_e32 v50, 0x60, v65
	ds_read2st64_b32 v[50:51], v50 offset0:12 offset1:13
	v_mul_f32_e32 v53, v68, v52
	v_fma_f32 v53, v66, v72, -v53
	s_waitcnt lgkmcnt(0)
	v_add_f32_e32 v53, v53, v50
	v_mul_f32_e32 v50, v66, v52
	v_fmac_f32_e32 v50, v68, v72
	v_add_f32_e32 v52, v50, v51
	s_nop 0
	v_cvt_pk_bf16_f32 v50, v53, v1
	ds_write_b16 v82, v50 offset:10080
	s_nop 0
	v_cvt_pk_bf16_f32 v50, v52, v1
	ds_write_b16 v82, v50 offset:10208
	v_add_u32_e32 v50, 0x70, v65
	ds_read2st64_b32 v[50:51], v50 offset0:14 offset1:15
	v_mul_f32_e32 v72, v68, v52
	v_fma_f32 v72, v66, v53, -v72
	s_waitcnt lgkmcnt(0)
	v_add_f32_e32 v72, v72, v50
	v_mul_f32_e32 v50, v66, v52
	v_fmac_f32_e32 v50, v68, v53
	v_add_f32_e32 v52, v50, v51
	s_nop 0
	v_cvt_pk_bf16_f32 v50, v72, v1
	ds_write_b16 v82, v50 offset:10352
	s_nop 0
	v_cvt_pk_bf16_f32 v50, v52, v1
	ds_write_b16 v82, v50 offset:10480
	v_add_u32_e32 v50, 0x80, v65
	ds_read2st64_b32 v[50:51], v50 offset0:16 offset1:17
	v_mul_f32_e32 v53, v68, v52
	v_fma_f32 v53, v66, v72, -v53
	s_waitcnt lgkmcnt(0)
	v_add_f32_e32 v53, v53, v50
	v_mul_f32_e32 v50, v66, v52
	v_fmac_f32_e32 v50, v68, v72
	v_add_f32_e32 v52, v50, v51
	s_nop 0
	v_cvt_pk_bf16_f32 v50, v53, v1
	ds_write_b16 v82, v50 offset:10624
	s_nop 0
	v_cvt_pk_bf16_f32 v50, v52, v1
	ds_write_b16 v82, v50 offset:10752
	v_add_u32_e32 v50, 0x90, v65
	ds_read2st64_b32 v[50:51], v50 offset0:18 offset1:19
	v_mul_f32_e32 v72, v68, v52
	v_fma_f32 v72, v66, v53, -v72
	s_waitcnt lgkmcnt(0)
; #define LAS __attribute__((address_space(3)))
; __device__ __forceinline__ float bf2f(bf16_t b) { return __uint_as_float(((unsigned)b) << 16); }
; __device__ __forceinline__ bf16_t f2bf(float f) { return (bf16_t)(cvt_pk_bf16(f, 0.f) & 0xffffu); }
; #define LDS_FENCE() asm volatile("s_waitcnt lgkmcnt(0)" ::: "memory")
; template <bool OUT>
; __device__ __forceinline__ void s5_item(KP P, int l, int item, int lane, LAS unsigned char* ldsw) {
;     ...
;         if (OUT) {
;             LDS_FENCE();
;             f32x4 y = {0.f, 0.f, 0.f, 0.f};
; #pragma unroll
;             for (int ks = 0; ks < 4; ++ks) { const bf16x8 af = *(const LAS bf16x8*)(xL + fr * 136 + ks * 32 + fq * 8); y = __builtin_amdgcn_mfma_f32_16x16x32_bf16(af, cfr[ks], y, 0, 0, 0); }
; #pragma unroll
;             for (int j = 0; j < 4; ++j) { const size_t trow = (size_t)(tb + fq * 4 + j);
;                 const float uu = bf2f(proj[trow * NP + O_DU + g * 16 + fr]);
;                 ((bf16_t*)(P->ws + W_YD))[trow * 512 + g * 16 + fr] = f2bf(gelu_tanh(y[j] + dsk * uu)); }
	v_add_f32_e32 v72, v72, v50
	v_mul_f32_e32 v50, v66, v52
	v_fmac_f32_e32 v50, v68, v53
	v_add_f32_e32 v52, v50, v51
	s_nop 0
	v_cvt_pk_bf16_f32 v50, v72, v1
	ds_write_b16 v82, v50 offset:10896
	s_nop 0
	v_cvt_pk_bf16_f32 v50, v52, v1
	ds_write_b16 v82, v50 offset:11024
	v_add_u32_e32 v50, 0xa0, v65
	ds_read2st64_b32 v[50:51], v50 offset0:20 offset1:21
	v_mul_f32_e32 v53, v68, v52
	v_fma_f32 v53, v66, v72, -v53
	s_waitcnt lgkmcnt(0)
	v_add_f32_e32 v53, v53, v50
	v_mul_f32_e32 v50, v66, v52
	v_fmac_f32_e32 v50, v68, v72
	v_add_f32_e32 v52, v50, v51
	s_nop 0
	v_cvt_pk_bf16_f32 v50, v53, v1
	ds_write_b16 v82, v50 offset:11168
	s_nop 0
	v_cvt_pk_bf16_f32 v50, v52, v1
	ds_write_b16 v82, v50 offset:11296
	v_add_u32_e32 v50, 0xb0, v65
	ds_read2st64_b32 v[50:51], v50 offset0:22 offset1:23
	v_mul_f32_e32 v72, v68, v52
	v_fma_f32 v72, v66, v53, -v72
	s_waitcnt lgkmcnt(0)
	v_add_f32_e32 v72, v72, v50
	v_mul_f32_e32 v50, v66, v52
	v_fmac_f32_e32 v50, v68, v53
	v_add_f32_e32 v53, v50, v51
	s_nop 0
	v_cvt_pk_bf16_f32 v50, v72, v1
	ds_write_b16 v82, v50 offset:11440
	s_nop 0
	v_cvt_pk_bf16_f32 v50, v53, v1
	ds_write_b16 v82, v50 offset:11568
	v_add_u32_e32 v50, 0xc0, v65
	ds_read2st64_b32 v[50:51], v50 offset0:24 offset1:25
	v_mul_f32_e32 v52, v68, v53
	v_mul_f32_e32 v53, v66, v53
	v_fma_f32 v52, v66, v72, -v52
	v_fmac_f32_e32 v53, v68, v72
	s_waitcnt lgkmcnt(0)
	v_pk_add_f32 v[50:51], v[52:53], v[50:51]
	s_nop 0
	s_nop 0
	v_cvt_pk_bf16_f32 v52, v50, v1
	ds_write_b16 v82, v52 offset:11712
	s_nop 0
	v_cvt_pk_bf16_f32 v52, v51, v1
	ds_write_b16 v82, v52 offset:11840
	v_add_u32_e32 v52, 0xd0, v65
	ds_read2st64_b32 v[52:53], v52 offset0:26 offset1:27
	v_pk_mul_f32 v[72:73], v[68:69], v[50:51]
	s_nop 0
	v_pk_fma_f32 v[74:75], v[66:67], v[50:51], v[72:73] op_sel:[0,0,1] op_sel_hi:[1,1,0] neg_lo:[0,0,1] neg_hi:[0,0,1]
	v_pk_fma_f32 v[50:51], v[66:67], v[50:51], v[72:73] op_sel:[0,0,1] op_sel_hi:[1,1,0]
	s_nop 0
	v_mov_b32_e32 v75, v51
	s_waitcnt lgkmcnt(0)
	v_pk_add_f32 v[50:51], v[74:75], v[52:53]
	s_nop 0
	s_nop 0
	v_cvt_pk_bf16_f32 v52, v50, v1
	ds_write_b16 v82, v52 offset:11984
	s_nop 0
	v_cvt_pk_bf16_f32 v52, v51, v1
	ds_write_b16 v82, v52 offset:12112
	v_add_u32_e32 v52, 0xe0, v65
	ds_read2st64_b32 v[52:53], v52 offset0:28 offset1:29
	v_pk_mul_f32 v[72:73], v[68:69], v[50:51]
	s_nop 0
	v_pk_fma_f32 v[74:75], v[66:67], v[50:51], v[72:73] op_sel:[0,0,1] op_sel_hi:[1,1,0] neg_lo:[0,0,1] neg_hi:[0,0,1]
	v_pk_fma_f32 v[50:51], v[66:67], v[50:51], v[72:73] op_sel:[0,0,1] op_sel_hi:[1,1,0]
	s_nop 0
	v_mov_b32_e32 v75, v51
	s_waitcnt lgkmcnt(0)
	v_pk_add_f32 v[50:51], v[74:75], v[52:53]
	s_nop 0
	s_nop 0
	v_cvt_pk_bf16_f32 v52, v50, v1
	ds_write_b16 v82, v52 offset:12256
	s_nop 0
	v_cvt_pk_bf16_f32 v52, v51, v1
	ds_write_b16 v82, v52 offset:12384
	v_add_u32_e32 v52, 0xf0, v65
	ds_read2st64_b32 v[52:53], v52 offset0:30 offset1:31
	v_pk_mul_f32 v[72:73], v[68:69], v[50:51]
	s_nop 0
	v_pk_fma_f32 v[74:75], v[66:67], v[50:51], v[72:73] op_sel:[0,0,1] op_sel_hi:[1,1,0] neg_lo:[0,0,1] neg_hi:[0,0,1]
	v_pk_fma_f32 v[50:51], v[66:67], v[50:51], v[72:73] op_sel:[0,0,1] op_sel_hi:[1,1,0]
	s_nop 0
	v_mov_b32_e32 v75, v51
	s_waitcnt lgkmcnt(0)
	v_pk_add_f32 v[72:73], v[74:75], v[52:53]
	s_nop 0
	s_nop 0
	v_cvt_pk_bf16_f32 v50, v72, v1
	ds_write_b16 v82, v50 offset:12528
	s_nop 0
	v_cvt_pk_bf16_f32 v50, v73, v1
	ds_write_b16 v82, v50 offset:12656
	s_waitcnt lgkmcnt(0)
	ds_read_b128 v[50:53], v81 offset:8448
	ds_read_b128 v[74:77], v81 offset:8512
	s_waitcnt lgkmcnt(1)
	v_mfma_f32_16x16x32_bf16 v[50:53], v[50:53], v[34:37], 0
	s_waitcnt lgkmcnt(0)
	v_mfma_f32_16x16x32_bf16 v[50:53], v[74:77], v[38:41], v[50:53]
	ds_read_b128 v[74:77], v81 offset:8576
	s_waitcnt lgkmcnt(0)
	v_mfma_f32_16x16x32_bf16 v[50:53], v[74:77], v[42:45], v[50:53]
	ds_read_b128 v[74:77], v81 offset:8640
	s_waitcnt lgkmcnt(0)
	v_mfma_f32_16x16x32_bf16 v[50:53], v[74:77], v[46:49], v[50:53]
	v_mov_b64_e32 v[76:77], s[24:25]
	v_mad_i64_i32 v[74:75], s[20:21], v78, s26, v[76:77]
	v_lshl_add_u64 v[86:87], v[74:75], 0, v[0:1]
	v_lshlrev_b32_e32 v74, 1, v56
	v_mov_b32_e32 v75, v1
	v_lshl_add_u64 v[86:87], v[86:87], 0, v[74:75]
	v_add_co_u32_e32 v86, vcc, s12, v86
	s_nop 1
	v_addc_co_u32_e32 v87, vcc, 0, v87, vcc
	global_load_ushort v85, v[86:87], off offset:272
	v_add_co_u32_e32 v106, vcc, s26, v86
	s_nop 1
	v_addc_co_u32_e32 v107, vcc, 0, v87, vcc
	global_load_ushort v110, v[106:107], off offset:272
	v_add_co_u32_e32 v106, vcc, s26, v106
	s_nop 1
	v_addc_co_u32_e32 v107, vcc, 0, v107, vcc
	global_load_ushort v111, v[106:107], off offset:272
	v_add_co_u32_e32 v106, vcc, s26, v106
	s_nop 1
	v_addc_co_u32_e32 v107, vcc, 0, v107, vcc
	global_load_ushort v112, v[106:107], off offset:272
	v_lshlrev_b64 v[86:87], 10, v[78:79]
	v_lshl_add_u64 v[86:87], v[70:71], 0, v[86:87]
	s_waitcnt vmcnt(0)
; __device__ __forceinline__ float bf2f(bf16_t b) { return __uint_as_float(((unsigned)b) << 16); }
; __device__ __forceinline__ bf16_t f2bf(float f) { return (bf16_t)(cvt_pk_bf16(f, 0.f) & 0xffffu); }
; template <bool OUT>
; __device__ __forceinline__ void s5_item(KP P, int l, int item, int lane, LAS unsigned char* ldsw) {
;     ...
;         const int tb = c * 64 + sub * 16;
;         u32x4 uw = {0u, 0u, 0u, 0u};
;         if (fq < 2) uw = *(const u32x4*)(proj + (size_t)(tb + fr) * NP + O_DU + g * 16 + fq * 8);
;         const bf16x8 ua = __builtin_bit_cast(bf16x8, uw);
;     ...
;             for (int j = 0; j < 4; ++j) { const size_t trow = (size_t)(tb + fq * 4 + j);
;                 const float uu = bf2f(proj[trow * NP + O_DU + g * 16 + fr]);
;                 ((bf16_t*)(P->ws + W_YD))[trow * 512 + g * 16 + fr] = f2bf(gelu_tanh(y[j] + dsk * uu)); }
	v_lshlrev_b32_e32 v85, 16, v85
	v_fma_f32 v50, v63, v85, v50
	v_mul_f32_e32 v85, 0x3d372713, v50
	v_mul_f32_e32 v85, v50, v85
	v_fma_f32 v85, v50, v85, v50
	v_mul_f32_e32 v85, 0x3f4c422a, v85
	v_add_f32_e32 v85, v85, v85
	v_mul_f32_e32 v85, 0x3fb8aa3b, v85
	v_exp_f32_e32 v85, v85
	v_mul_f32_e32 v50, 0.5, v50
	v_add_f32_e32 v85, 1.0, v85
	v_rcp_f32_e32 v85, v85
	s_nop 0
	v_fma_f32 v85, v85, -2.0, 1.0
	v_add_f32_e32 v85, 1.0, v85
	v_mul_f32_e32 v50, v50, v85
	s_nop 0
	v_cvt_pk_bf16_f32 v50, v50, v1
	global_store_short v[86:87], v50, off
	v_add_u32_e32 v86, 1, v78
	v_mad_i64_i32 v[88:89], s[20:21], v86, s26, v[76:77]
	v_lshl_add_u64 v[88:89], v[88:89], 0, v[0:1]
	v_lshl_add_u64 v[88:89], v[88:89], 0, v[74:75]
	v_add_co_u32_e32 v88, vcc, s12, v88
	v_ashrrev_i32_e32 v87, 31, v86
	s_nop 0
	v_addc_co_u32_e32 v89, vcc, 0, v89, vcc
	v_mov_b32_e32 v50, v110
	v_lshlrev_b32_e32 v50, 16, v50
	v_fma_f32 v50, v63, v50, v51
	v_mul_f32_e32 v51, 0x3d372713, v50
	v_mul_f32_e32 v51, v50, v51
	v_fma_f32 v51, v50, v51, v50
	v_mul_f32_e32 v51, 0x3f4c422a, v51
	v_add_f32_e32 v51, v51, v51
	v_mul_f32_e32 v51, 0x3fb8aa3b, v51
	v_exp_f32_e32 v51, v51
	v_mul_f32_e32 v50, 0.5, v50
	v_add_f32_e32 v51, 1.0, v51
	v_rcp_f32_e32 v51, v51
	s_nop 0
	v_fma_f32 v51, v51, -2.0, 1.0
	v_add_f32_e32 v51, 1.0, v51
	v_mul_f32_e32 v50, v50, v51
	s_nop 0
	v_cvt_pk_bf16_f32 v79, v50, v1
	v_lshlrev_b64 v[50:51], 10, v[86:87]
	v_lshl_add_u64 v[50:51], v[70:71], 0, v[50:51]
	global_store_short v[50:51], v79, off
	v_add_u32_e32 v50, 2, v78
	v_mad_i64_i32 v[86:87], s[20:21], v50, s26, v[76:77]
	v_lshl_add_u64 v[86:87], v[86:87], 0, v[0:1]
	v_lshl_add_u64 v[86:87], v[86:87], 0, v[74:75]
	v_add_co_u32_e32 v86, vcc, s12, v86
	v_ashrrev_i32_e32 v51, 31, v50
	s_nop 0
	v_addc_co_u32_e32 v87, vcc, 0, v87, vcc
	v_lshlrev_b64 v[50:51], 10, v[50:51]
	v_lshl_add_u64 v[50:51], v[70:71], 0, v[50:51]
	v_mov_b32_e32 v79, v111
	v_lshlrev_b32_e32 v79, 16, v79
	v_fma_f32 v52, v63, v79, v52
	v_mul_f32_e32 v79, 0x3d372713, v52
	v_mul_f32_e32 v79, v52, v79
	v_fma_f32 v79, v52, v79, v52
	v_mul_f32_e32 v79, 0x3f4c422a, v79
	v_add_f32_e32 v79, v79, v79
	v_mul_f32_e32 v79, 0x3fb8aa3b, v79
	v_exp_f32_e32 v79, v79
	v_mul_f32_e32 v52, 0.5, v52
	v_add_f32_e32 v79, 1.0, v79
	v_rcp_f32_e32 v79, v79
	s_nop 0
	v_fma_f32 v79, v79, -2.0, 1.0
	v_add_f32_e32 v79, 1.0, v79
	v_mul_f32_e32 v52, v52, v79
	s_nop 0
	v_cvt_pk_bf16_f32 v52, v52, v1
	global_store_short v[50:51], v52, off
	v_add_u32_e32 v50, 3, v78
	v_mad_i64_i32 v[76:77], s[20:21], v50, s26, v[76:77]
	v_lshl_add_u64 v[76:77], v[76:77], 0, v[0:1]
	v_lshl_add_u64 v[74:75], v[76:77], 0, v[74:75]
	v_add_co_u32_e32 v74, vcc, s12, v74
	v_ashrrev_i32_e32 v51, 31, v50
	s_nop 0
	v_addc_co_u32_e32 v75, vcc, 0, v75, vcc
	v_lshlrev_b64 v[50:51], 10, v[50:51]
	v_lshl_add_u64 v[50:51], v[70:71], 0, v[50:51]
	v_mov_b32_e32 v0, v112
	v_lshlrev_b32_e32 v0, 16, v0
	v_fmac_f32_e32 v53, v63, v0
	v_mul_f32_e32 v0, 0x3d372713, v53
	v_mul_f32_e32 v0, v53, v0
	v_fma_f32 v0, v53, v0, v53
	v_mul_f32_e32 v0, 0x3f4c422a, v0
	v_add_f32_e32 v0, v0, v0
	v_mul_f32_e32 v0, 0x3fb8aa3b, v0
	v_exp_f32_e32 v0, v0
	v_mul_f32_e32 v52, 0.5, v53
	v_add_f32_e32 v0, 1.0, v0
	v_rcp_f32_e32 v0, v0
	s_nop 0
	v_fma_f32 v0, v0, -2.0, 1.0
	v_add_f32_e32 v0, 1.0, v0
	v_mul_f32_e32 v0, v52, v0
	s_nop 0
	v_cvt_pk_bf16_f32 v0, v0, v1
	global_store_short v[50:51], v0, off
	s_waitcnt lgkmcnt(0)
	s_cbranch_scc0 .LBB0_1073
.LBB0_1104:
	s_waitcnt vmcnt(4)
	v_mov_b32_e32 v50, v100
	v_lshlrev_b32_e32 v0, 1, v64
	v_mov_b32_e32 v51, v101
	v_mov_b32_e32 v52, v102
	v_mov_b32_e32 v53, v103
	s_cmp_eq_u32 s30, 48
	s_cbranch_scc1 .Lmy_s5b_nopf
	v_mov_b32_e32 v100, 0
	v_mov_b32_e32 v101, 0
	v_mov_b32_e32 v102, 0
	v_mov_b32_e32 v103, 0
	s_and_saveexec_b64 s[20:21], s[42:43]
	s_cbranch_execz .Lmy_s5b_pf1
	v_lshlrev_b32_e32 v104, 1, v64
	v_mov_b32_e32 v105, v1
	v_add3_u32 v102, s30, v84, 16
	v_mov_b64_e32 v[100:101], s[24:25]
	v_mad_i64_i32 v[100:101], s[44:45], v102, s26, v[100:101]
	v_lshl_add_u64 v[100:101], v[100:101], 0, v[104:105]
	v_lshlrev_b32_e32 v102, 1, v58
	v_mov_b32_e32 v103, v1
	v_lshl_add_u64 v[100:101], v[100:101], 0, v[102:103]
	v_add_co_u32_e32 v100, vcc, 0x4000, v100
	s_nop 1
	v_addc_co_u32_e32 v101, vcc, 0, v101, vcc
	global_load_dwordx4 v[100:103], v[100:101], off offset:272
